# parallel hand-written fill_rowscales also for the token-major mixer in-projection (3 units per thread-half, all loads in flight)
# speedup vs baseline: 1.0135x; 1.0019x over previous
; #define LAS __attribute__((address_space(3)))
;     __host__ __device__ bool next(int i, Unit& u) const {
;         const long L = (long)i * G + c; if (L >= nwg) return false;
;         int wgid = (int)L; { const int q = nwg / NXCD, r = nwg % NXCD, xcd = wgid % NXCD, off = wgid / NXCD; wgid = (xcd < r ? xcd * (q + 1) : r * (q + 1) + (xcd - r) * q) + off; }
;         const int nig = WGM * nN, gid = wgid / nig, fm = gid * WGM, gsz = (nM - fm) < WGM ? (nM - fm) : WGM;
;         u.pm = fm + ((wgid % nig) % gsz); u.pn = (wgid % nig) / gsz; return true;
;     }
; __device__ __forceinline__ u32x4 pk8(const f32x4 a, const f32x4 b) { u32x4 w; w.x = pk2(a[0], a[1]); w.y = pk2(a[2], a[3]); w.z = pk2(b[0], b[1]); w.w = pk2(b[2], b[3]); return w; }
; __device__ __forceinline__ float rowscale(const float* SS, int row) {
;     const f32x4* p = (const f32x4*)(SS + (size_t)row * 16);
;     const f32x4 a = p[0], b = p[1], c = p[2], d = p[3];
;     const float s = ((a[0] + a[1]) + (a[2] + a[3])) + ((b[0] + b[1]) + (b[2] + b[3])) + ((c[0] + c[1]) + (c[2] + c[3])) + ((d[0] + d[1]) + (d[2] + d[3]));
;     return 1.0f / sqrtf(s * (1.0f / 1024.0f) + 1e-6f);
; }
; DI void fill_rowscales(const pg8::StaticOrder& S, const float* SS, LAS float* rs, int bycol) {
;     pg8::Unit u;
;     for (int ui = 0; ui < RS_SLOTS && S.next(ui, u); ++ui) {
;         const int t = threadIdx.x;
;         if (t < 256) rs[ui * 256 + t] = pg8::rowscale(SS, (bycol ? u.pn : u.pm) * 256 + t);
;     }
;     __syncthreads();
; }
.LBB0_492:
	s_add_u32 s12, s90, 0x5900000
	s_waitcnt vmcnt(0)
	v_lshlrev_b32_e32 v2, 2, v254
	s_addc_u32 s13, s91, 0
	s_ashr_i32 s3, s2, 31
	s_movk_i32 s0, 0x100
	v_add_u32_e32 v0, 0, v2
	s_ashr_i32 s46, s94, 31
	s_mov_b32 s47, s94
	v_cmp_gt_u32_e64 s[0:1], s0, v254
	v_add_u32_e32 v153, 0x20000, v0
	s_movk_i32 s14, 0xd000
	s_waitcnt lgkmcnt(0)
	v_mov_b64_e32 v[0:1], 0x47f
	s_movk_i32 s15, 0x91
	v_mov_b32_e32 v3, 0x358637bd
	s_mov_b32 s16, 0xf800000
	v_mov_b32_e32 v4, 0x260
	s_mov_b64 s[6:7], s[2:3]
	v_readfirstlane_b32 s17, v254
	v_and_b32_e32 v5, 0xff, v254
	s_nop 3
	s_lshr_b32 s17, s17, 8
	s_mul_i32 s18, s17, s47
	s_add_i32 s6, s2, s18
	s_lshl_b32 s7, s47, 1
	s_cmp_lt_u32 s6, 0x480
	s_cselect_b32 s4, s6, s2
	s_and_b32 s5, s4, 7
	s_lshr_b32 s4, s4, 3
	s_mul_i32 s5, s5, 0x90
	s_add_i32 s4, s4, s5
	s_mul_hi_u32 s5, s4, 0x38e38e4
	s_and_b32 s18, s4, 7
	s_lshl_b32 s5, s5, 3
	s_add_i32 s5, s5, s18
	v_lshl_or_b32 v26, s5, 8, v5
	v_lshlrev_b32_e32 v26, 6, v26
	s_add_i32 s6, s6, s7
	global_load_dwordx4 v[32:35], v26, s[12:13]
	global_load_dwordx4 v[36:39], v26, s[12:13] offset:16
	global_load_dwordx4 v[40:43], v26, s[12:13] offset:32
	global_load_dwordx4 v[44:47], v26, s[12:13] offset:48
	s_cmp_lt_u32 s6, 0x480
	s_cselect_b32 s4, s6, s2
	s_and_b32 s5, s4, 7
	s_lshr_b32 s4, s4, 3
	s_mul_i32 s5, s5, 0x90
	s_add_i32 s4, s4, s5
	s_mul_hi_u32 s5, s4, 0x38e38e4
	s_and_b32 s18, s4, 7
	s_lshl_b32 s5, s5, 3
	s_add_i32 s5, s5, s18
	v_lshl_or_b32 v27, s5, 8, v5
	v_lshlrev_b32_e32 v27, 6, v27
	s_add_i32 s6, s6, s7
	global_load_dwordx4 v[48:51], v27, s[12:13]
	global_load_dwordx4 v[52:55], v27, s[12:13] offset:16
	global_load_dwordx4 v[56:59], v27, s[12:13] offset:32
	global_load_dwordx4 v[60:63], v27, s[12:13] offset:48
	s_cmp_lt_u32 s6, 0x480
	s_cselect_b32 s4, s6, s2
	s_and_b32 s5, s4, 7
	s_lshr_b32 s4, s4, 3
	s_mul_i32 s5, s5, 0x90
	s_add_i32 s4, s4, s5
	s_mul_hi_u32 s5, s4, 0x38e38e4
	s_and_b32 s18, s4, 7
	s_lshl_b32 s5, s5, 3
	s_add_i32 s5, s5, s18
	v_lshl_or_b32 v28, s5, 8, v5
	v_lshlrev_b32_e32 v28, 6, v28
	s_add_i32 s6, s6, s7
	global_load_dwordx4 v[64:67], v28, s[12:13]
	global_load_dwordx4 v[68:71], v28, s[12:13] offset:16
	global_load_dwordx4 v[72:75], v28, s[12:13] offset:32
	global_load_dwordx4 v[76:79], v28, s[12:13] offset:48
	s_waitcnt vmcnt(8)
	v_add_f32_e32 v9, v32, v33
	v_add_f32_e32 v13, v34, v35
	v_add_f32_e32 v9, v9, v13
	v_add_f32_e32 v10, v36, v37
	v_add_f32_e32 v13, v38, v39
	v_add_f32_e32 v10, v10, v13
	v_add_f32_e32 v11, v40, v41
	v_add_f32_e32 v13, v42, v43
	v_add_f32_e32 v11, v11, v13
	v_add_f32_e32 v12, v44, v45
	v_add_f32_e32 v13, v46, v47
	v_add_f32_e32 v12, v12, v13
	v_add_f32_e32 v9, v9, v10
	v_add_f32_e32 v9, v9, v11
	v_add_f32_e32 v9, v9, v12
	v_fmamk_f32 v9, v9, 0x3a800000, v3
	v_mul_f32_e32 v10, 0x4f800000, v9
	v_cmp_gt_f32_e32 vcc, s16, v9
	s_nop 1
	v_cndmask_b32_e32 v9, v9, v10, vcc
	v_sqrt_f32_e32 v10, v9
	s_nop 0
	v_add_u32_e32 v11, -1, v10
	v_add_u32_e32 v12, 1, v10
	v_fma_f32 v13, -v11, v10, v9
	v_fma_f32 v14, -v12, v10, v9
	v_cmp_ge_f32_e64 s[4:5], 0, v13
	s_nop 1
	v_cndmask_b32_e64 v10, v10, v11, s[4:5]
	v_cmp_lt_f32_e64 s[4:5], 0, v14
	s_nop 1
	v_cndmask_b32_e64 v10, v10, v12, s[4:5]
	v_mul_f32_e32 v11, 0x37800000, v10
	v_cndmask_b32_e32 v10, v10, v11, vcc
	v_cmp_class_f32_e32 vcc, v9, v4
	s_nop 1
	v_cndmask_b32_e32 v9, v10, v9, vcc
	v_div_scale_f32 v10, s[4:5], v9, v9, 1.0
	v_rcp_f32_e32 v11, v10
	v_div_scale_f32 v12, vcc, 1.0, v9, 1.0
	v_fma_f32 v13, -v10, v11, 1.0
	v_fmac_f32_e32 v11, v13, v11
	v_mul_f32_e32 v13, v12, v11
	v_fma_f32 v14, -v10, v13, v12
	v_fmac_f32_e32 v13, v14, v11
	v_fma_f32 v10, -v10, v13, v12
	v_div_fmas_f32 v10, v10, v11, v13
	v_div_fixup_f32 v9, v10, v9, 1.0
	ds_write_b32 v153, v9
	s_waitcnt vmcnt(4)
	v_add_f32_e32 v9, v48, v49
	v_add_f32_e32 v13, v50, v51
	v_add_f32_e32 v9, v9, v13
	v_add_f32_e32 v10, v52, v53
	v_add_f32_e32 v13, v54, v55
	v_add_f32_e32 v10, v10, v13
	v_add_f32_e32 v11, v56, v57
	v_add_f32_e32 v13, v58, v59
	v_add_f32_e32 v11, v11, v13
	v_add_f32_e32 v12, v60, v61
	v_add_f32_e32 v13, v62, v63
	v_add_f32_e32 v12, v12, v13
	v_add_f32_e32 v9, v9, v10
	v_add_f32_e32 v9, v9, v11
	v_add_f32_e32 v9, v9, v12
	v_fmamk_f32 v9, v9, 0x3a800000, v3
	v_mul_f32_e32 v10, 0x4f800000, v9
	v_cmp_gt_f32_e32 vcc, s16, v9
	s_nop 1
	v_cndmask_b32_e32 v9, v9, v10, vcc
	v_sqrt_f32_e32 v10, v9
	s_nop 0
	v_add_u32_e32 v11, -1, v10
	v_add_u32_e32 v12, 1, v10
	v_fma_f32 v13, -v11, v10, v9
	v_fma_f32 v14, -v12, v10, v9
	v_cmp_ge_f32_e64 s[4:5], 0, v13
	s_nop 1
	v_cndmask_b32_e64 v10, v10, v11, s[4:5]
	v_cmp_lt_f32_e64 s[4:5], 0, v14
	s_nop 1
	v_cndmask_b32_e64 v10, v10, v12, s[4:5]
	v_mul_f32_e32 v11, 0x37800000, v10
	v_cndmask_b32_e32 v10, v10, v11, vcc
	v_cmp_class_f32_e32 vcc, v9, v4
	s_nop 1
	v_cndmask_b32_e32 v9, v10, v9, vcc
	v_div_scale_f32 v10, s[4:5], v9, v9, 1.0
	v_rcp_f32_e32 v11, v10
	v_div_scale_f32 v12, vcc, 1.0, v9, 1.0
	v_fma_f32 v13, -v10, v11, 1.0
	v_fmac_f32_e32 v11, v13, v11
	v_mul_f32_e32 v13, v12, v11
	v_fma_f32 v14, -v10, v13, v12
	v_fmac_f32_e32 v13, v14, v11
	v_fma_f32 v10, -v10, v13, v12
	v_div_fmas_f32 v10, v10, v11, v13
	v_div_fixup_f32 v9, v10, v9, 1.0
	ds_write_b32 v153, v9 offset:2048
	s_waitcnt vmcnt(0)
	v_add_f32_e32 v9, v64, v65
	v_add_f32_e32 v13, v66, v67
	v_add_f32_e32 v9, v9, v13
	v_add_f32_e32 v10, v68, v69
	v_add_f32_e32 v13, v70, v71
	v_add_f32_e32 v10, v10, v13
	v_add_f32_e32 v11, v72, v73
	v_add_f32_e32 v13, v74, v75
	v_add_f32_e32 v11, v11, v13
	v_add_f32_e32 v12, v76, v77
	v_add_f32_e32 v13, v78, v79
	v_add_f32_e32 v12, v12, v13
	v_add_f32_e32 v9, v9, v10
	v_add_f32_e32 v9, v9, v11
	v_add_f32_e32 v9, v9, v12
	v_fmamk_f32 v9, v9, 0x3a800000, v3
	v_mul_f32_e32 v10, 0x4f800000, v9
	v_cmp_gt_f32_e32 vcc, s16, v9
	s_nop 1
	v_cndmask_b32_e32 v9, v9, v10, vcc
	v_sqrt_f32_e32 v10, v9
	s_nop 0
	v_add_u32_e32 v11, -1, v10
	v_add_u32_e32 v12, 1, v10
	v_fma_f32 v13, -v11, v10, v9
	v_fma_f32 v14, -v12, v10, v9
	v_cmp_ge_f32_e64 s[4:5], 0, v13
	s_nop 1
	v_cndmask_b32_e64 v10, v10, v11, s[4:5]
	v_cmp_lt_f32_e64 s[4:5], 0, v14
	s_nop 1
	v_cndmask_b32_e64 v10, v10, v12, s[4:5]
	v_mul_f32_e32 v11, 0x37800000, v10
	v_cndmask_b32_e32 v10, v10, v11, vcc
	v_cmp_class_f32_e32 vcc, v9, v4
	s_nop 1
	v_cndmask_b32_e32 v9, v10, v9, vcc
	v_div_scale_f32 v10, s[4:5], v9, v9, 1.0
	v_rcp_f32_e32 v11, v10
	v_div_scale_f32 v12, vcc, 1.0, v9, 1.0
	v_fma_f32 v13, -v10, v11, 1.0
	v_fmac_f32_e32 v11, v13, v11
	v_mul_f32_e32 v13, v12, v11
	v_fma_f32 v14, -v10, v13, v12
	v_fmac_f32_e32 v13, v14, v11
	v_fma_f32 v10, -v10, v13, v12
	v_div_fmas_f32 v10, v10, v11, v13
	v_div_fixup_f32 v9, v10, v9, 1.0
	ds_write_b32 v153, v9 offset:4096
